# bf16 GEMM epilogues (5 multi-unit instances): the leading half converts and issues its first six output stores before the alignment barrier, using the store path while the trailing half finishes its l
# baseline (speedup 1.0000x reference)
.Lpk495_exit:
	v_lshl_add_u32 v152, s43, 8, v146
	v_lshl_or_b32 v144, s42, 8, v148
	v_readlane_b32 s2, v252, 2
	v_ashrrev_i32_e32 v145, 31, v144
	v_readlane_b32 s3, v252, 3
	v_ashrrev_i32_e32 v153, 31, v152
	v_pk_add_f32 v[128:129], v[128:129], 0 op_sel_hi:[1,0]
	v_lshl_add_u64 v[154:155], v[144:145], 1, s[2:3]
	v_lshlrev_b64 v[144:145], 11, v[152:153]
	v_lshl_add_u64 v[144:145], v[154:155], 0, v[144:145]
	v_pk_add_f32 v[126:127], v[126:127], 0 op_sel_hi:[1,0]
	v_pk_add_f32 v[156:157], v[124:125], 0 op_sel_hi:[1,0]
	v_pk_add_f32 v[124:125], v[122:123], 0 op_sel_hi:[1,0]
	v_cvt_pk_bf16_f32 v122, v126, v127
	v_cvt_pk_bf16_f32 v123, v128, v129
	v_pk_add_f32 v[118:119], v[118:119], 0 op_sel_hi:[1,0]
	v_cvt_pk_bf16_f32 v124, v124, v125
	v_cvt_pk_bf16_f32 v125, v156, v157
	global_store_dwordx4 v[144:145], v[122:125], off
	v_pk_add_f32 v[120:121], v[120:121], 0 op_sel_hi:[1,0]
	v_pk_add_f32 v[114:115], v[114:115], 0 op_sel_hi:[1,0]
	v_pk_add_f32 v[122:123], v[112:113], 0 op_sel_hi:[1,0]
	v_pk_add_f32 v[112:113], v[110:111], 0 op_sel_hi:[1,0]
	v_cvt_pk_bf16_f32 v110, v118, v119
	v_cvt_pk_bf16_f32 v111, v120, v121
	v_pk_add_f32 v[102:103], v[102:103], 0 op_sel_hi:[1,0]
	v_cvt_pk_bf16_f32 v112, v112, v113
	v_cvt_pk_bf16_f32 v113, v122, v123
	global_store_dwordx4 v[144:145], v[110:113], off offset:256
	v_pk_add_f32 v[104:105], v[104:105], 0 op_sel_hi:[1,0]
	v_pk_add_f32 v[98:99], v[98:99], 0 op_sel_hi:[1,0]
	v_or_b32_e32 v110, 16, v152
	v_ashrrev_i32_e32 v111, 31, v110
	v_lshlrev_b64 v[110:111], 11, v[110:111]
	v_lshl_add_u64 v[110:111], v[154:155], 0, v[110:111]
	v_pk_add_f32 v[112:113], v[116:117], 0 op_sel_hi:[1,0]
	v_pk_add_f32 v[116:117], v[108:109], 0 op_sel_hi:[1,0]
	v_pk_add_f32 v[108:109], v[106:107], 0 op_sel_hi:[1,0]
	v_cvt_pk_bf16_f32 v106, v114, v115
	v_cvt_pk_bf16_f32 v107, v112, v113
	v_pk_add_f32 v[86:87], v[86:87], 0 op_sel_hi:[1,0]
	v_cvt_pk_bf16_f32 v108, v108, v109
	v_cvt_pk_bf16_f32 v109, v116, v117
	global_store_dwordx4 v[110:111], v[106:109], off
	v_pk_add_f32 v[88:89], v[88:89], 0 op_sel_hi:[1,0]
	v_pk_add_f32 v[82:83], v[82:83], 0 op_sel_hi:[1,0]
	v_pk_add_f32 v[106:107], v[96:97], 0 op_sel_hi:[1,0]
	v_pk_add_f32 v[96:97], v[94:95], 0 op_sel_hi:[1,0]
	v_cvt_pk_bf16_f32 v94, v102, v103
	v_cvt_pk_bf16_f32 v95, v104, v105
	v_pk_add_f32 v[72:73], v[72:73], 0 op_sel_hi:[1,0]
	v_cvt_pk_bf16_f32 v96, v96, v97
	v_cvt_pk_bf16_f32 v97, v106, v107
	global_store_dwordx4 v[110:111], v[94:97], off offset:256
	v_pk_add_f32 v[70:71], v[70:71], 0 op_sel_hi:[1,0]
	s_mov_b64 s[2:3], 0x40000
	v_or_b32_e32 v94, 32, v152
	v_ashrrev_i32_e32 v95, 31, v94
	v_lshlrev_b64 v[94:95], 11, v[94:95]
	v_lshl_add_u64 v[94:95], v[154:155], 0, v[94:95]
	v_pk_add_f32 v[96:97], v[100:101], 0 op_sel_hi:[1,0]
	v_pk_add_f32 v[100:101], v[92:93], 0 op_sel_hi:[1,0]
	v_pk_add_f32 v[92:93], v[90:91], 0 op_sel_hi:[1,0]
	v_cvt_pk_bf16_f32 v90, v98, v99
	v_cvt_pk_bf16_f32 v91, v96, v97
	v_pk_add_f32 v[62:63], v[62:63], 0 op_sel_hi:[1,0]
	v_cvt_pk_bf16_f32 v92, v92, v93
	v_cvt_pk_bf16_f32 v93, v100, v101
	global_store_dwordx4 v[94:95], v[90:93], off
	v_pk_add_f32 v[64:65], v[64:65], 0 op_sel_hi:[1,0]
	v_pk_add_f32 v[56:57], v[56:57], 0 op_sel_hi:[1,0]
	v_pk_add_f32 v[90:91], v[80:81], 0 op_sel_hi:[1,0]
	v_pk_add_f32 v[80:81], v[78:79], 0 op_sel_hi:[1,0]
	v_cvt_pk_bf16_f32 v78, v86, v87
	v_cvt_pk_bf16_f32 v79, v88, v89
	v_pk_add_f32 v[54:55], v[54:55], 0 op_sel_hi:[1,0]
	v_cvt_pk_bf16_f32 v80, v80, v81
	v_cvt_pk_bf16_f32 v81, v90, v91
	global_store_dwordx4 v[94:95], v[78:81], off offset:256
	s_and_b64 vcc, exec, s[6:7]
	s_cbranch_vccz .LBB0_498
	s_barrier
.LBB0_498:
	v_pk_add_f32 v[50:51], v[50:51], 0 op_sel_hi:[1,0]
	v_pk_add_f32 v[40:41], v[40:41], 0 op_sel_hi:[1,0]
	v_or_b32_e32 v78, 48, v152
	v_ashrrev_i32_e32 v79, 31, v78
	v_lshlrev_b64 v[78:79], 11, v[78:79]
	v_lshl_add_u64 v[78:79], v[154:155], 0, v[78:79]
	v_pk_add_f32 v[80:81], v[84:85], 0 op_sel_hi:[1,0]
	v_pk_add_f32 v[84:85], v[76:77], 0 op_sel_hi:[1,0]
	v_pk_add_f32 v[76:77], v[74:75], 0 op_sel_hi:[1,0]
	v_cvt_pk_bf16_f32 v74, v82, v83
	v_cvt_pk_bf16_f32 v75, v80, v81
	v_pk_add_f32 v[38:39], v[38:39], 0 op_sel_hi:[1,0]
	v_cvt_pk_bf16_f32 v76, v76, v77
	v_cvt_pk_bf16_f32 v77, v84, v85
	global_store_dwordx4 v[78:79], v[74:77], off
	v_pk_add_f32 v[34:35], v[34:35], 0 op_sel_hi:[1,0]
	v_pk_add_f32 v[24:25], v[24:25], 0 op_sel_hi:[1,0]
	v_pk_add_f32 v[74:75], v[68:69], 0 op_sel_hi:[1,0]
	v_pk_add_f32 v[68:69], v[66:67], 0 op_sel_hi:[1,0]
	v_cvt_pk_bf16_f32 v66, v70, v71
	v_cvt_pk_bf16_f32 v67, v72, v73
	v_pk_add_f32 v[22:23], v[22:23], 0 op_sel_hi:[1,0]
	v_cvt_pk_bf16_f32 v68, v68, v69
	v_cvt_pk_bf16_f32 v69, v74, v75
	global_store_dwordx4 v[78:79], v[66:69], off offset:256
	v_pk_add_f32 v[18:19], v[18:19], 0 op_sel_hi:[1,0]
	v_pk_add_f32 v[8:9], v[8:9], 0 op_sel_hi:[1,0]
	v_lshl_add_u64 v[66:67], v[144:145], 0, s[2:3]
	s_mov_b32 s2, 0x40000
	v_pk_add_f32 v[68:69], v[60:61], 0 op_sel_hi:[1,0]
	v_pk_add_f32 v[60:61], v[58:59], 0 op_sel_hi:[1,0]
	v_cvt_pk_bf16_f32 v58, v62, v63
	v_add_co_u32_e32 v62, vcc, s2, v144
	v_cvt_pk_bf16_f32 v59, v64, v65
	v_cvt_pk_bf16_f32 v60, v60, v61
	v_cvt_pk_bf16_f32 v61, v68, v69
	s_mov_b64 s[2:3], 0x48000
	s_nop 0
	v_addc_co_u32_e32 v63, vcc, 0, v145, vcc
	global_store_dwordx4 v[62:63], v[58:61], off
	v_pk_add_f32 v[6:7], v[6:7], 0 op_sel_hi:[1,0]
	s_nop 0
	v_pk_add_f32 v[58:59], v[48:49], 0 op_sel_hi:[1,0]
	v_pk_add_f32 v[48:49], v[46:47], 0 op_sel_hi:[1,0]
	v_cvt_pk_bf16_f32 v46, v54, v55
	v_cvt_pk_bf16_f32 v47, v56, v57
	s_nop 0
	v_cvt_pk_bf16_f32 v48, v48, v49
	v_cvt_pk_bf16_f32 v49, v58, v59
	global_store_dwordx4 v[66:67], v[46:49], off offset:256
	s_nop 1
	v_lshl_add_u64 v[46:47], v[144:145], 0, s[2:3]
	v_pk_add_f32 v[48:49], v[52:53], 0 op_sel_hi:[1,0]
	s_mov_b32 s2, 0x48000
	v_pk_add_f32 v[52:53], v[44:45], 0 op_sel_hi:[1,0]
	v_pk_add_f32 v[44:45], v[42:43], 0 op_sel_hi:[1,0]
	v_cvt_pk_bf16_f32 v42, v50, v51
	v_cvt_pk_bf16_f32 v43, v48, v49
	v_add_co_u32_e32 v48, vcc, s2, v144
	v_cvt_pk_bf16_f32 v44, v44, v45
	v_cvt_pk_bf16_f32 v45, v52, v53
	s_mov_b64 s[2:3], 0x50000
	s_nop 0
	v_addc_co_u32_e32 v49, vcc, 0, v145, vcc
	global_store_dwordx4 v[48:49], v[42:45], off
	s_nop 1
	v_pk_add_f32 v[42:43], v[32:33], 0 op_sel_hi:[1,0]
	v_pk_add_f32 v[32:33], v[30:31], 0 op_sel_hi:[1,0]
	v_cvt_pk_bf16_f32 v30, v38, v39
	v_cvt_pk_bf16_f32 v31, v40, v41
	s_nop 0
	v_cvt_pk_bf16_f32 v32, v32, v33
	v_cvt_pk_bf16_f32 v33, v42, v43
	global_store_dwordx4 v[46:47], v[30:33], off offset:256
	s_nop 1
	v_lshl_add_u64 v[30:31], v[144:145], 0, s[2:3]
	v_pk_add_f32 v[32:33], v[36:37], 0 op_sel_hi:[1,0]
	s_mov_b32 s2, 0x50000
	v_pk_add_f32 v[36:37], v[28:29], 0 op_sel_hi:[1,0]
	v_pk_add_f32 v[28:29], v[26:27], 0 op_sel_hi:[1,0]
	v_cvt_pk_bf16_f32 v26, v34, v35
	v_cvt_pk_bf16_f32 v27, v32, v33
	v_add_co_u32_e32 v32, vcc, s2, v144
	v_cvt_pk_bf16_f32 v28, v28, v29
	v_cvt_pk_bf16_f32 v29, v36, v37
	s_mov_b64 s[2:3], 0x58000
	s_nop 0
	v_addc_co_u32_e32 v33, vcc, 0, v145, vcc
	global_store_dwordx4 v[32:33], v[26:29], off
	s_nop 1
	v_pk_add_f32 v[26:27], v[16:17], 0 op_sel_hi:[1,0]
	v_pk_add_f32 v[16:17], v[14:15], 0 op_sel_hi:[1,0]
	v_cvt_pk_bf16_f32 v14, v22, v23
	v_cvt_pk_bf16_f32 v15, v24, v25
	s_nop 0
	v_cvt_pk_bf16_f32 v16, v16, v17
	v_cvt_pk_bf16_f32 v17, v26, v27
	global_store_dwordx4 v[30:31], v[14:17], off offset:256
	s_nop 1
	v_lshl_add_u64 v[14:15], v[144:145], 0, s[2:3]
	v_pk_add_f32 v[16:17], v[20:21], 0 op_sel_hi:[1,0]
	s_mov_b32 s2, 0x58000
	v_pk_add_f32 v[20:21], v[12:13], 0 op_sel_hi:[1,0]
	v_pk_add_f32 v[12:13], v[10:11], 0 op_sel_hi:[1,0]
	v_cvt_pk_bf16_f32 v10, v18, v19
	v_cvt_pk_bf16_f32 v11, v16, v17
	v_add_co_u32_e32 v16, vcc, s2, v144
	v_cvt_pk_bf16_f32 v12, v12, v13
	v_cvt_pk_bf16_f32 v13, v20, v21
	s_mov_b64 s[2:3], -1
	s_nop 0
	v_addc_co_u32_e32 v17, vcc, 0, v145, vcc
	global_store_dwordx4 v[16:17], v[10:13], off
	s_andn2_b64 vcc, exec, s[12:13]
	s_nop 0
	v_pk_add_f32 v[10:11], v[4:5], 0 op_sel_hi:[1,0]
	v_pk_add_f32 v[4:5], v[2:3], 0 op_sel_hi:[1,0]
	v_cvt_pk_bf16_f32 v2, v6, v7
	v_cvt_pk_bf16_f32 v3, v8, v9
	s_nop 0
	v_cvt_pk_bf16_f32 v4, v4, v5
	v_cvt_pk_bf16_f32 v5, v10, v11
	global_store_dwordx4 v[14:15], v[2:5], off offset:256
	s_cbranch_vccnz .LBB0_486
	s_andn2_b64 vcc, exec, s[4:5]
	s_cbranch_vccnz .LBB0_485
	s_barrier
	s_branch .LBB0_485

.Lpk555_exit:
	v_lshl_or_b32 v144, s47, 8, v150
	v_ashrrev_i32_e32 v145, 31, v144
	v_lshl_add_u32 v158, s24, 8, v148
	v_lshl_add_u64 v[144:145], v[144:145], 1, s[62:63]
	v_mad_i64_i32 v[154:155], s[2:3], v158, s46, v[144:145]
	v_pk_add_f32 v[128:129], v[128:129], 0 op_sel_hi:[1,0]
	v_pk_add_f32 v[126:127], v[126:127], 0 op_sel_hi:[1,0]
	v_pk_add_f32 v[156:157], v[124:125], 0 op_sel_hi:[1,0]
	v_pk_add_f32 v[124:125], v[122:123], 0 op_sel_hi:[1,0]
	v_cvt_pk_bf16_f32 v122, v126, v127
	v_cvt_pk_bf16_f32 v123, v128, v129
	v_pk_add_f32 v[118:119], v[118:119], 0 op_sel_hi:[1,0]
	v_cvt_pk_bf16_f32 v124, v124, v125
	v_cvt_pk_bf16_f32 v125, v156, v157
	global_store_dwordx4 v[154:155], v[122:125], off
	v_pk_add_f32 v[120:121], v[120:121], 0 op_sel_hi:[1,0]
	v_pk_add_f32 v[114:115], v[114:115], 0 op_sel_hi:[1,0]
	v_pk_add_f32 v[122:123], v[112:113], 0 op_sel_hi:[1,0]
	v_pk_add_f32 v[112:113], v[110:111], 0 op_sel_hi:[1,0]
	v_cvt_pk_bf16_f32 v110, v118, v119
	v_cvt_pk_bf16_f32 v111, v120, v121
	v_pk_add_f32 v[102:103], v[102:103], 0 op_sel_hi:[1,0]
	v_cvt_pk_bf16_f32 v112, v112, v113
	v_cvt_pk_bf16_f32 v113, v122, v123
	global_store_dwordx4 v[154:155], v[110:113], off offset:256
	v_pk_add_f32 v[104:105], v[104:105], 0 op_sel_hi:[1,0]
	v_pk_add_f32 v[98:99], v[98:99], 0 op_sel_hi:[1,0]
	v_or_b32_e32 v110, 16, v158
	v_mad_i64_i32 v[110:111], s[2:3], v110, s46, v[144:145]
	v_pk_add_f32 v[112:113], v[116:117], 0 op_sel_hi:[1,0]
	v_pk_add_f32 v[116:117], v[108:109], 0 op_sel_hi:[1,0]
	v_pk_add_f32 v[108:109], v[106:107], 0 op_sel_hi:[1,0]
	v_cvt_pk_bf16_f32 v106, v114, v115
	v_cvt_pk_bf16_f32 v107, v112, v113
	v_pk_add_f32 v[86:87], v[86:87], 0 op_sel_hi:[1,0]
	v_cvt_pk_bf16_f32 v108, v108, v109
	v_cvt_pk_bf16_f32 v109, v116, v117
	global_store_dwordx4 v[110:111], v[106:109], off
	v_pk_add_f32 v[88:89], v[88:89], 0 op_sel_hi:[1,0]
	v_pk_add_f32 v[82:83], v[82:83], 0 op_sel_hi:[1,0]
	v_pk_add_f32 v[106:107], v[96:97], 0 op_sel_hi:[1,0]
	v_pk_add_f32 v[96:97], v[94:95], 0 op_sel_hi:[1,0]
	v_cvt_pk_bf16_f32 v94, v102, v103
	v_cvt_pk_bf16_f32 v95, v104, v105
	v_pk_add_f32 v[70:71], v[70:71], 0 op_sel_hi:[1,0]
	v_cvt_pk_bf16_f32 v96, v96, v97
	v_cvt_pk_bf16_f32 v97, v106, v107
	global_store_dwordx4 v[110:111], v[94:97], off offset:256
	v_pk_add_f32 v[72:73], v[72:73], 0 op_sel_hi:[1,0]
	v_pk_add_f32 v[64:65], v[64:65], 0 op_sel_hi:[1,0]
	v_or_b32_e32 v94, 32, v158
	v_mad_i64_i32 v[94:95], s[2:3], v94, s46, v[144:145]
	v_pk_add_f32 v[96:97], v[100:101], 0 op_sel_hi:[1,0]
	v_pk_add_f32 v[100:101], v[92:93], 0 op_sel_hi:[1,0]
	v_pk_add_f32 v[92:93], v[90:91], 0 op_sel_hi:[1,0]
	v_cvt_pk_bf16_f32 v90, v98, v99
	v_cvt_pk_bf16_f32 v91, v96, v97
	v_pk_add_f32 v[62:63], v[62:63], 0 op_sel_hi:[1,0]
	v_cvt_pk_bf16_f32 v92, v92, v93
	v_cvt_pk_bf16_f32 v93, v100, v101
	global_store_dwordx4 v[94:95], v[90:93], off
	v_pk_add_f32 v[54:55], v[54:55], 0 op_sel_hi:[1,0]
	v_pk_add_f32 v[56:57], v[56:57], 0 op_sel_hi:[1,0]
	v_pk_add_f32 v[90:91], v[80:81], 0 op_sel_hi:[1,0]
	v_pk_add_f32 v[80:81], v[78:79], 0 op_sel_hi:[1,0]
	v_cvt_pk_bf16_f32 v78, v86, v87
	v_cvt_pk_bf16_f32 v79, v88, v89
	v_pk_add_f32 v[50:51], v[50:51], 0 op_sel_hi:[1,0]
	v_cvt_pk_bf16_f32 v80, v80, v81
	v_cvt_pk_bf16_f32 v81, v90, v91
	global_store_dwordx4 v[94:95], v[78:81], off offset:256
	s_and_b64 vcc, exec, s[8:9]
	s_cbranch_vccz .LBB0_558
	s_barrier
.LBB0_558:
	v_pk_add_f32 v[38:39], v[38:39], 0 op_sel_hi:[1,0]
	v_pk_add_f32 v[40:41], v[40:41], 0 op_sel_hi:[1,0]
	v_or_b32_e32 v78, 48, v158
	v_mad_i64_i32 v[78:79], s[2:3], v78, s46, v[144:145]
	v_pk_add_f32 v[80:81], v[84:85], 0 op_sel_hi:[1,0]
	v_pk_add_f32 v[84:85], v[76:77], 0 op_sel_hi:[1,0]
	v_pk_add_f32 v[76:77], v[74:75], 0 op_sel_hi:[1,0]
	v_cvt_pk_bf16_f32 v74, v82, v83
	v_cvt_pk_bf16_f32 v75, v80, v81
	v_pk_add_f32 v[34:35], v[34:35], 0 op_sel_hi:[1,0]
	v_cvt_pk_bf16_f32 v76, v76, v77
	v_cvt_pk_bf16_f32 v77, v84, v85
	global_store_dwordx4 v[78:79], v[74:77], off
	v_pk_add_f32 v[22:23], v[22:23], 0 op_sel_hi:[1,0]
	v_pk_add_f32 v[24:25], v[24:25], 0 op_sel_hi:[1,0]
	v_pk_add_f32 v[74:75], v[68:69], 0 op_sel_hi:[1,0]
	v_pk_add_f32 v[68:69], v[66:67], 0 op_sel_hi:[1,0]
	v_cvt_pk_bf16_f32 v66, v70, v71
	v_cvt_pk_bf16_f32 v67, v72, v73
	v_pk_add_f32 v[18:19], v[18:19], 0 op_sel_hi:[1,0]
	v_cvt_pk_bf16_f32 v68, v68, v69
	v_cvt_pk_bf16_f32 v69, v74, v75
	global_store_dwordx4 v[78:79], v[66:69], off offset:256
	s_andn2_b64 vcc, exec, s[18:19]
	v_pk_add_f32 v[8:9], v[8:9], 0 op_sel_hi:[1,0]
	v_add_u32_e32 v66, 0x80, v158
	v_mad_i64_i32 v[66:67], s[2:3], v66, s46, v[144:145]
	v_pk_add_f32 v[68:69], v[60:61], 0 op_sel_hi:[1,0]
	v_pk_add_f32 v[60:61], v[58:59], 0 op_sel_hi:[1,0]
	v_cvt_pk_bf16_f32 v58, v62, v63
	v_cvt_pk_bf16_f32 v59, v64, v65
	v_pk_add_f32 v[6:7], v[6:7], 0 op_sel_hi:[1,0]
	v_cvt_pk_bf16_f32 v60, v60, v61
	v_cvt_pk_bf16_f32 v61, v68, v69
	global_store_dwordx4 v[66:67], v[58:61], off
	s_nop 1
	v_pk_add_f32 v[58:59], v[48:49], 0 op_sel_hi:[1,0]
	v_pk_add_f32 v[48:49], v[46:47], 0 op_sel_hi:[1,0]
	v_cvt_pk_bf16_f32 v46, v54, v55
	v_cvt_pk_bf16_f32 v47, v56, v57
	s_nop 0
	v_cvt_pk_bf16_f32 v48, v48, v49
	v_cvt_pk_bf16_f32 v49, v58, v59
	global_store_dwordx4 v[66:67], v[46:49], off offset:256
	s_nop 1
	v_add_u32_e32 v46, 0x90, v158
	v_mad_i64_i32 v[46:47], s[2:3], v46, s46, v[144:145]
	v_pk_add_f32 v[48:49], v[52:53], 0 op_sel_hi:[1,0]
	v_pk_add_f32 v[52:53], v[44:45], 0 op_sel_hi:[1,0]
	v_pk_add_f32 v[44:45], v[42:43], 0 op_sel_hi:[1,0]
	v_cvt_pk_bf16_f32 v42, v50, v51
	v_cvt_pk_bf16_f32 v43, v48, v49
	s_nop 0
	v_cvt_pk_bf16_f32 v44, v44, v45
	v_cvt_pk_bf16_f32 v45, v52, v53
	global_store_dwordx4 v[46:47], v[42:45], off
	s_nop 1
	v_pk_add_f32 v[42:43], v[32:33], 0 op_sel_hi:[1,0]
	v_pk_add_f32 v[32:33], v[30:31], 0 op_sel_hi:[1,0]
	v_cvt_pk_bf16_f32 v30, v38, v39
	v_cvt_pk_bf16_f32 v31, v40, v41
	s_nop 0
	v_cvt_pk_bf16_f32 v32, v32, v33
	v_cvt_pk_bf16_f32 v33, v42, v43
	global_store_dwordx4 v[46:47], v[30:33], off offset:256
	s_nop 1
	v_add_u32_e32 v30, 0xa0, v158
	v_mad_i64_i32 v[30:31], s[2:3], v30, s46, v[144:145]
	v_pk_add_f32 v[32:33], v[36:37], 0 op_sel_hi:[1,0]
	v_pk_add_f32 v[36:37], v[28:29], 0 op_sel_hi:[1,0]
	v_pk_add_f32 v[28:29], v[26:27], 0 op_sel_hi:[1,0]
	v_cvt_pk_bf16_f32 v26, v34, v35
	v_cvt_pk_bf16_f32 v27, v32, v33
	s_nop 0
	v_cvt_pk_bf16_f32 v28, v28, v29
	v_cvt_pk_bf16_f32 v29, v36, v37
	global_store_dwordx4 v[30:31], v[26:29], off
	s_nop 1
	v_pk_add_f32 v[26:27], v[16:17], 0 op_sel_hi:[1,0]
	v_pk_add_f32 v[16:17], v[14:15], 0 op_sel_hi:[1,0]
	v_cvt_pk_bf16_f32 v14, v22, v23
	v_cvt_pk_bf16_f32 v15, v24, v25
	s_nop 0
	v_cvt_pk_bf16_f32 v16, v16, v17
	v_cvt_pk_bf16_f32 v17, v26, v27
	global_store_dwordx4 v[30:31], v[14:17], off offset:256
	s_nop 1
	v_add_u32_e32 v14, 0xb0, v158
	v_mad_i64_i32 v[14:15], s[2:3], v14, s46, v[144:145]
	v_pk_add_f32 v[16:17], v[20:21], 0 op_sel_hi:[1,0]
	v_pk_add_f32 v[20:21], v[12:13], 0 op_sel_hi:[1,0]
	v_pk_add_f32 v[12:13], v[10:11], 0 op_sel_hi:[1,0]
	v_cvt_pk_bf16_f32 v10, v18, v19
	v_cvt_pk_bf16_f32 v11, v16, v17
	s_mov_b64 s[2:3], -1
	v_cvt_pk_bf16_f32 v12, v12, v13
	v_cvt_pk_bf16_f32 v13, v20, v21
	global_store_dwordx4 v[14:15], v[10:13], off
	s_nop 1
	v_pk_add_f32 v[10:11], v[4:5], 0 op_sel_hi:[1,0]
	v_pk_add_f32 v[4:5], v[2:3], 0 op_sel_hi:[1,0]
	v_cvt_pk_bf16_f32 v2, v6, v7
	v_cvt_pk_bf16_f32 v3, v8, v9
	s_nop 0
	v_cvt_pk_bf16_f32 v4, v4, v5
	v_cvt_pk_bf16_f32 v5, v10, v11
	global_store_dwordx4 v[14:15], v[2:5], off offset:256
	s_cbranch_vccnz .LBB0_550
	s_andn2_b64 vcc, exec, s[0:1]
	s_cbranch_vccnz .LBB0_549
	s_barrier
	s_branch .LBB0_549

.Lpk1098_exit:
	v_lshl_add_u32 v152, s28, 8, v1
	v_lshl_or_b32 v144, s51, 8, v147
	v_readlane_b32 s2, v252, 2
	v_ashrrev_i32_e32 v145, 31, v144
	v_readlane_b32 s3, v252, 3
	v_ashrrev_i32_e32 v153, 31, v152
	v_pk_add_f32 v[128:129], v[128:129], 0 op_sel_hi:[1,0]
	v_lshl_add_u64 v[154:155], v[144:145], 1, s[2:3]
	v_lshlrev_b64 v[144:145], 11, v[152:153]
	v_lshl_add_u64 v[144:145], v[154:155], 0, v[144:145]
	v_pk_add_f32 v[126:127], v[126:127], 0 op_sel_hi:[1,0]
	v_pk_add_f32 v[156:157], v[124:125], 0 op_sel_hi:[1,0]
	v_pk_add_f32 v[124:125], v[122:123], 0 op_sel_hi:[1,0]
	v_cvt_pk_bf16_f32 v122, v126, v127
	v_cvt_pk_bf16_f32 v123, v128, v129
	v_pk_add_f32 v[118:119], v[118:119], 0 op_sel_hi:[1,0]
	v_cvt_pk_bf16_f32 v124, v124, v125
	v_cvt_pk_bf16_f32 v125, v156, v157
	global_store_dwordx4 v[144:145], v[122:125], off
	v_pk_add_f32 v[120:121], v[120:121], 0 op_sel_hi:[1,0]
	v_pk_add_f32 v[114:115], v[114:115], 0 op_sel_hi:[1,0]
	v_pk_add_f32 v[122:123], v[112:113], 0 op_sel_hi:[1,0]
	v_pk_add_f32 v[112:113], v[110:111], 0 op_sel_hi:[1,0]
	v_cvt_pk_bf16_f32 v110, v118, v119
	v_cvt_pk_bf16_f32 v111, v120, v121
	v_pk_add_f32 v[102:103], v[102:103], 0 op_sel_hi:[1,0]
	v_cvt_pk_bf16_f32 v112, v112, v113
	v_cvt_pk_bf16_f32 v113, v122, v123
	global_store_dwordx4 v[144:145], v[110:113], off offset:256
	v_pk_add_f32 v[104:105], v[104:105], 0 op_sel_hi:[1,0]
	v_pk_add_f32 v[98:99], v[98:99], 0 op_sel_hi:[1,0]
	v_or_b32_e32 v110, 16, v152
	v_ashrrev_i32_e32 v111, 31, v110
	v_lshlrev_b64 v[110:111], 11, v[110:111]
	v_lshl_add_u64 v[110:111], v[154:155], 0, v[110:111]
	v_pk_add_f32 v[112:113], v[116:117], 0 op_sel_hi:[1,0]
	v_pk_add_f32 v[116:117], v[108:109], 0 op_sel_hi:[1,0]
	v_pk_add_f32 v[108:109], v[106:107], 0 op_sel_hi:[1,0]
	v_cvt_pk_bf16_f32 v106, v114, v115
	v_cvt_pk_bf16_f32 v107, v112, v113
	v_pk_add_f32 v[86:87], v[86:87], 0 op_sel_hi:[1,0]
	v_cvt_pk_bf16_f32 v108, v108, v109
	v_cvt_pk_bf16_f32 v109, v116, v117
	global_store_dwordx4 v[110:111], v[106:109], off
	v_pk_add_f32 v[88:89], v[88:89], 0 op_sel_hi:[1,0]
	v_pk_add_f32 v[82:83], v[82:83], 0 op_sel_hi:[1,0]
	v_pk_add_f32 v[106:107], v[96:97], 0 op_sel_hi:[1,0]
	v_pk_add_f32 v[96:97], v[94:95], 0 op_sel_hi:[1,0]
	v_cvt_pk_bf16_f32 v94, v102, v103
	v_cvt_pk_bf16_f32 v95, v104, v105
	v_pk_add_f32 v[72:73], v[72:73], 0 op_sel_hi:[1,0]
	v_cvt_pk_bf16_f32 v96, v96, v97
	v_cvt_pk_bf16_f32 v97, v106, v107
	global_store_dwordx4 v[110:111], v[94:97], off offset:256
	v_pk_add_f32 v[70:71], v[70:71], 0 op_sel_hi:[1,0]
	s_mov_b64 s[2:3], 0x40000
	v_or_b32_e32 v94, 32, v152
	v_ashrrev_i32_e32 v95, 31, v94
	v_lshlrev_b64 v[94:95], 11, v[94:95]
	v_lshl_add_u64 v[94:95], v[154:155], 0, v[94:95]
	v_pk_add_f32 v[96:97], v[100:101], 0 op_sel_hi:[1,0]
	v_pk_add_f32 v[100:101], v[92:93], 0 op_sel_hi:[1,0]
	v_pk_add_f32 v[92:93], v[90:91], 0 op_sel_hi:[1,0]
	v_cvt_pk_bf16_f32 v90, v98, v99
	v_cvt_pk_bf16_f32 v91, v96, v97
	v_pk_add_f32 v[62:63], v[62:63], 0 op_sel_hi:[1,0]
	v_cvt_pk_bf16_f32 v92, v92, v93
	v_cvt_pk_bf16_f32 v93, v100, v101
	global_store_dwordx4 v[94:95], v[90:93], off
	v_pk_add_f32 v[64:65], v[64:65], 0 op_sel_hi:[1,0]
	v_pk_add_f32 v[56:57], v[56:57], 0 op_sel_hi:[1,0]
	v_pk_add_f32 v[90:91], v[80:81], 0 op_sel_hi:[1,0]
	v_pk_add_f32 v[80:81], v[78:79], 0 op_sel_hi:[1,0]
	v_cvt_pk_bf16_f32 v78, v86, v87
	v_cvt_pk_bf16_f32 v79, v88, v89
	v_pk_add_f32 v[54:55], v[54:55], 0 op_sel_hi:[1,0]
	v_cvt_pk_bf16_f32 v80, v80, v81
	v_cvt_pk_bf16_f32 v81, v90, v91
	global_store_dwordx4 v[94:95], v[78:81], off offset:256
	s_and_b64 vcc, exec, s[8:9]
	s_cbranch_vccz .LBB0_1101
	s_barrier
.LBB0_1101:
	v_pk_add_f32 v[50:51], v[50:51], 0 op_sel_hi:[1,0]
	v_pk_add_f32 v[40:41], v[40:41], 0 op_sel_hi:[1,0]
	v_or_b32_e32 v78, 48, v152
	v_ashrrev_i32_e32 v79, 31, v78
	v_lshlrev_b64 v[78:79], 11, v[78:79]
	v_lshl_add_u64 v[78:79], v[154:155], 0, v[78:79]
	v_pk_add_f32 v[80:81], v[84:85], 0 op_sel_hi:[1,0]
	v_pk_add_f32 v[84:85], v[76:77], 0 op_sel_hi:[1,0]
	v_pk_add_f32 v[76:77], v[74:75], 0 op_sel_hi:[1,0]
	v_cvt_pk_bf16_f32 v74, v82, v83
	v_cvt_pk_bf16_f32 v75, v80, v81
	v_pk_add_f32 v[38:39], v[38:39], 0 op_sel_hi:[1,0]
	v_cvt_pk_bf16_f32 v76, v76, v77
	v_cvt_pk_bf16_f32 v77, v84, v85
	global_store_dwordx4 v[78:79], v[74:77], off
	v_pk_add_f32 v[34:35], v[34:35], 0 op_sel_hi:[1,0]
	v_pk_add_f32 v[24:25], v[24:25], 0 op_sel_hi:[1,0]
	v_pk_add_f32 v[74:75], v[68:69], 0 op_sel_hi:[1,0]
	v_pk_add_f32 v[68:69], v[66:67], 0 op_sel_hi:[1,0]
	v_cvt_pk_bf16_f32 v66, v70, v71
	v_cvt_pk_bf16_f32 v67, v72, v73
	v_pk_add_f32 v[22:23], v[22:23], 0 op_sel_hi:[1,0]
	v_cvt_pk_bf16_f32 v68, v68, v69
	v_cvt_pk_bf16_f32 v69, v74, v75
	global_store_dwordx4 v[78:79], v[66:69], off offset:256
	v_pk_add_f32 v[18:19], v[18:19], 0 op_sel_hi:[1,0]
	v_pk_add_f32 v[8:9], v[8:9], 0 op_sel_hi:[1,0]
	v_lshl_add_u64 v[66:67], v[144:145], 0, s[2:3]
	s_mov_b32 s2, 0x40000
	v_pk_add_f32 v[68:69], v[60:61], 0 op_sel_hi:[1,0]
	v_pk_add_f32 v[60:61], v[58:59], 0 op_sel_hi:[1,0]
	v_cvt_pk_bf16_f32 v58, v62, v63
	v_add_co_u32_e32 v62, vcc, s2, v144
	v_cvt_pk_bf16_f32 v59, v64, v65
	v_cvt_pk_bf16_f32 v60, v60, v61
	v_cvt_pk_bf16_f32 v61, v68, v69
	s_mov_b64 s[2:3], 0x48000
	s_nop 0
	v_addc_co_u32_e32 v63, vcc, 0, v145, vcc
	global_store_dwordx4 v[62:63], v[58:61], off
	v_pk_add_f32 v[6:7], v[6:7], 0 op_sel_hi:[1,0]
	s_nop 0
	v_pk_add_f32 v[58:59], v[48:49], 0 op_sel_hi:[1,0]
	v_pk_add_f32 v[48:49], v[46:47], 0 op_sel_hi:[1,0]
	v_cvt_pk_bf16_f32 v46, v54, v55
	v_cvt_pk_bf16_f32 v47, v56, v57
	s_nop 0
	v_cvt_pk_bf16_f32 v48, v48, v49
	v_cvt_pk_bf16_f32 v49, v58, v59
	global_store_dwordx4 v[66:67], v[46:49], off offset:256
	s_nop 1
	v_lshl_add_u64 v[46:47], v[144:145], 0, s[2:3]
	v_pk_add_f32 v[48:49], v[52:53], 0 op_sel_hi:[1,0]
	s_mov_b32 s2, 0x48000
	v_pk_add_f32 v[52:53], v[44:45], 0 op_sel_hi:[1,0]
	v_pk_add_f32 v[44:45], v[42:43], 0 op_sel_hi:[1,0]
	v_cvt_pk_bf16_f32 v42, v50, v51
	v_cvt_pk_bf16_f32 v43, v48, v49
	v_add_co_u32_e32 v48, vcc, s2, v144
	v_cvt_pk_bf16_f32 v44, v44, v45
	v_cvt_pk_bf16_f32 v45, v52, v53
	s_mov_b64 s[2:3], -1
	s_nop 0
	v_addc_co_u32_e32 v49, vcc, 0, v145, vcc
	global_store_dwordx4 v[48:49], v[42:45], off
	s_nop 1
	v_pk_add_f32 v[42:43], v[32:33], 0 op_sel_hi:[1,0]
	v_pk_add_f32 v[32:33], v[30:31], 0 op_sel_hi:[1,0]
	v_cvt_pk_bf16_f32 v30, v38, v39
	v_cvt_pk_bf16_f32 v31, v40, v41
	s_nop 0
	v_cvt_pk_bf16_f32 v32, v32, v33
	v_cvt_pk_bf16_f32 v33, v42, v43
	global_store_dwordx4 v[46:47], v[30:33], off offset:256
	s_nop 1
	v_pk_add_f32 v[32:33], v[36:37], 0 op_sel_hi:[1,0]
	v_pk_add_f32 v[36:37], v[28:29], 0 op_sel_hi:[1,0]
	v_pk_add_f32 v[28:29], v[26:27], 0 op_sel_hi:[1,0]
	v_cvt_pk_bf16_f32 v26, v34, v35
	v_cvt_pk_bf16_f32 v27, v32, v33
	v_add_co_u32_e32 v32, vcc, s49, v144
	v_cvt_pk_bf16_f32 v28, v28, v29
	v_cvt_pk_bf16_f32 v29, v36, v37
	v_lshl_add_u64 v[30:31], v[144:145], 0, s[10:11]
	s_nop 0
	v_addc_co_u32_e32 v33, vcc, 0, v145, vcc
	global_store_dwordx4 v[32:33], v[26:29], off
	s_nop 1
	v_pk_add_f32 v[26:27], v[16:17], 0 op_sel_hi:[1,0]
	v_pk_add_f32 v[16:17], v[14:15], 0 op_sel_hi:[1,0]
	v_cvt_pk_bf16_f32 v14, v22, v23
	v_cvt_pk_bf16_f32 v15, v24, v25
	s_nop 0
	v_cvt_pk_bf16_f32 v16, v16, v17
	v_cvt_pk_bf16_f32 v17, v26, v27
	global_store_dwordx4 v[30:31], v[14:17], off offset:256
	s_nop 1
	v_pk_add_f32 v[16:17], v[20:21], 0 op_sel_hi:[1,0]
	v_pk_add_f32 v[20:21], v[12:13], 0 op_sel_hi:[1,0]
	v_pk_add_f32 v[12:13], v[10:11], 0 op_sel_hi:[1,0]
	v_cvt_pk_bf16_f32 v10, v18, v19
	v_cvt_pk_bf16_f32 v11, v16, v17
	v_add_co_u32_e32 v16, vcc, s50, v144
	v_lshl_add_u64 v[14:15], v[144:145], 0, s[12:13]
	s_nop 0
	v_addc_co_u32_e32 v17, vcc, 0, v145, vcc
	v_cvt_pk_bf16_f32 v12, v12, v13
	v_cvt_pk_bf16_f32 v13, v20, v21
	global_store_dwordx4 v[16:17], v[10:13], off
	s_andn2_b64 vcc, exec, s[22:23]
	s_nop 0
	v_pk_add_f32 v[10:11], v[4:5], 0 op_sel_hi:[1,0]
	v_pk_add_f32 v[4:5], v[2:3], 0 op_sel_hi:[1,0]
	v_cvt_pk_bf16_f32 v2, v6, v7
	v_cvt_pk_bf16_f32 v3, v8, v9
	s_nop 0
	v_cvt_pk_bf16_f32 v4, v4, v5
	v_cvt_pk_bf16_f32 v5, v10, v11
	global_store_dwordx4 v[14:15], v[2:5], off offset:256
	s_cbranch_vccnz .LBB0_1089
	s_andn2_b64 vcc, exec, s[4:5]
	s_cbranch_vccnz .LBB0_1088
	s_barrier
	s_branch .LBB0_1088

.Lpk1239_exit:
	v_lshl_add_u32 v152, s34, 8, v1
	v_lshl_or_b32 v144, s57, 8, v147
	v_readlane_b32 s2, v252, 2
	v_ashrrev_i32_e32 v145, 31, v144
	v_readlane_b32 s3, v252, 3
	v_ashrrev_i32_e32 v153, 31, v152
	v_pk_add_f32 v[128:129], v[128:129], 0 op_sel_hi:[1,0]
	v_lshl_add_u64 v[154:155], v[144:145], 1, s[2:3]
	v_lshlrev_b64 v[144:145], 11, v[152:153]
	v_lshl_add_u64 v[144:145], v[154:155], 0, v[144:145]
	v_pk_add_f32 v[126:127], v[126:127], 0 op_sel_hi:[1,0]
	v_pk_add_f32 v[156:157], v[124:125], 0 op_sel_hi:[1,0]
	v_pk_add_f32 v[124:125], v[122:123], 0 op_sel_hi:[1,0]
	v_cvt_pk_bf16_f32 v122, v126, v127
	v_cvt_pk_bf16_f32 v123, v128, v129
	v_pk_add_f32 v[118:119], v[118:119], 0 op_sel_hi:[1,0]
	v_cvt_pk_bf16_f32 v124, v124, v125
	v_cvt_pk_bf16_f32 v125, v156, v157
	global_store_dwordx4 v[144:145], v[122:125], off
	v_pk_add_f32 v[120:121], v[120:121], 0 op_sel_hi:[1,0]
	v_pk_add_f32 v[114:115], v[114:115], 0 op_sel_hi:[1,0]
	v_pk_add_f32 v[122:123], v[112:113], 0 op_sel_hi:[1,0]
	v_pk_add_f32 v[112:113], v[110:111], 0 op_sel_hi:[1,0]
	v_cvt_pk_bf16_f32 v110, v118, v119
	v_cvt_pk_bf16_f32 v111, v120, v121
	v_pk_add_f32 v[102:103], v[102:103], 0 op_sel_hi:[1,0]
	v_cvt_pk_bf16_f32 v112, v112, v113
	v_cvt_pk_bf16_f32 v113, v122, v123
	global_store_dwordx4 v[144:145], v[110:113], off offset:256
	v_pk_add_f32 v[104:105], v[104:105], 0 op_sel_hi:[1,0]
	v_pk_add_f32 v[98:99], v[98:99], 0 op_sel_hi:[1,0]
	v_or_b32_e32 v110, 16, v152
	v_ashrrev_i32_e32 v111, 31, v110
	v_lshlrev_b64 v[110:111], 11, v[110:111]
	v_lshl_add_u64 v[110:111], v[154:155], 0, v[110:111]
	v_pk_add_f32 v[112:113], v[116:117], 0 op_sel_hi:[1,0]
	v_pk_add_f32 v[116:117], v[108:109], 0 op_sel_hi:[1,0]
	v_pk_add_f32 v[108:109], v[106:107], 0 op_sel_hi:[1,0]
	v_cvt_pk_bf16_f32 v106, v114, v115
	v_cvt_pk_bf16_f32 v107, v112, v113
	v_pk_add_f32 v[86:87], v[86:87], 0 op_sel_hi:[1,0]
	v_cvt_pk_bf16_f32 v108, v108, v109
	v_cvt_pk_bf16_f32 v109, v116, v117
	global_store_dwordx4 v[110:111], v[106:109], off
	v_pk_add_f32 v[88:89], v[88:89], 0 op_sel_hi:[1,0]
	v_pk_add_f32 v[82:83], v[82:83], 0 op_sel_hi:[1,0]
	v_pk_add_f32 v[106:107], v[96:97], 0 op_sel_hi:[1,0]
	v_pk_add_f32 v[96:97], v[94:95], 0 op_sel_hi:[1,0]
	v_cvt_pk_bf16_f32 v94, v102, v103
	v_cvt_pk_bf16_f32 v95, v104, v105
	v_pk_add_f32 v[72:73], v[72:73], 0 op_sel_hi:[1,0]
	v_cvt_pk_bf16_f32 v96, v96, v97
	v_cvt_pk_bf16_f32 v97, v106, v107
	global_store_dwordx4 v[110:111], v[94:97], off offset:256
	v_pk_add_f32 v[70:71], v[70:71], 0 op_sel_hi:[1,0]
	v_pk_add_f32 v[62:63], v[62:63], 0 op_sel_hi:[1,0]
	v_or_b32_e32 v94, 32, v152
	v_ashrrev_i32_e32 v95, 31, v94
	v_lshlrev_b64 v[94:95], 11, v[94:95]
	v_lshl_add_u64 v[94:95], v[154:155], 0, v[94:95]
	v_pk_add_f32 v[96:97], v[100:101], 0 op_sel_hi:[1,0]
	v_pk_add_f32 v[100:101], v[92:93], 0 op_sel_hi:[1,0]
	v_pk_add_f32 v[92:93], v[90:91], 0 op_sel_hi:[1,0]
	v_cvt_pk_bf16_f32 v90, v98, v99
	v_cvt_pk_bf16_f32 v91, v96, v97
	v_pk_add_f32 v[64:65], v[64:65], 0 op_sel_hi:[1,0]
	v_cvt_pk_bf16_f32 v92, v92, v93
	v_cvt_pk_bf16_f32 v93, v100, v101
	global_store_dwordx4 v[94:95], v[90:93], off
	s_mov_b64 s[2:3], 0x40000
	v_pk_add_f32 v[56:57], v[56:57], 0 op_sel_hi:[1,0]
	v_pk_add_f32 v[90:91], v[80:81], 0 op_sel_hi:[1,0]
	v_pk_add_f32 v[80:81], v[78:79], 0 op_sel_hi:[1,0]
	v_cvt_pk_bf16_f32 v78, v86, v87
	v_cvt_pk_bf16_f32 v79, v88, v89
	v_pk_add_f32 v[54:55], v[54:55], 0 op_sel_hi:[1,0]
	v_cvt_pk_bf16_f32 v80, v80, v81
	v_cvt_pk_bf16_f32 v81, v90, v91
	global_store_dwordx4 v[94:95], v[78:81], off offset:256
	s_and_b64 vcc, exec, s[10:11]
	s_cbranch_vccz .LBB0_1242
	s_barrier
.LBB0_1242:
	v_pk_add_f32 v[50:51], v[50:51], 0 op_sel_hi:[1,0]
	v_pk_add_f32 v[40:41], v[40:41], 0 op_sel_hi:[1,0]
	v_or_b32_e32 v78, 48, v152
	v_ashrrev_i32_e32 v79, 31, v78
	v_lshlrev_b64 v[78:79], 11, v[78:79]
	v_lshl_add_u64 v[78:79], v[154:155], 0, v[78:79]
	v_pk_add_f32 v[80:81], v[84:85], 0 op_sel_hi:[1,0]
	v_pk_add_f32 v[84:85], v[76:77], 0 op_sel_hi:[1,0]
	v_pk_add_f32 v[76:77], v[74:75], 0 op_sel_hi:[1,0]
	v_cvt_pk_bf16_f32 v74, v82, v83
	v_cvt_pk_bf16_f32 v75, v80, v81
	v_pk_add_f32 v[38:39], v[38:39], 0 op_sel_hi:[1,0]
	v_cvt_pk_bf16_f32 v76, v76, v77
	v_cvt_pk_bf16_f32 v77, v84, v85
	global_store_dwordx4 v[78:79], v[74:77], off
	v_pk_add_f32 v[34:35], v[34:35], 0 op_sel_hi:[1,0]
	v_pk_add_f32 v[24:25], v[24:25], 0 op_sel_hi:[1,0]
	v_pk_add_f32 v[74:75], v[68:69], 0 op_sel_hi:[1,0]
	v_pk_add_f32 v[68:69], v[66:67], 0 op_sel_hi:[1,0]
	v_cvt_pk_bf16_f32 v66, v70, v71
	v_cvt_pk_bf16_f32 v67, v72, v73
	v_pk_add_f32 v[22:23], v[22:23], 0 op_sel_hi:[1,0]
	v_cvt_pk_bf16_f32 v68, v68, v69
	v_cvt_pk_bf16_f32 v69, v74, v75
	global_store_dwordx4 v[78:79], v[66:69], off offset:256
	v_pk_add_f32 v[18:19], v[18:19], 0 op_sel_hi:[1,0]
	v_pk_add_f32 v[8:9], v[8:9], 0 op_sel_hi:[1,0]
	v_pk_add_f32 v[68:69], v[60:61], 0 op_sel_hi:[1,0]
	v_pk_add_f32 v[60:61], v[58:59], 0 op_sel_hi:[1,0]
	v_cvt_pk_bf16_f32 v58, v62, v63
	v_add_co_u32_e32 v62, vcc, s53, v144
	v_cvt_pk_bf16_f32 v59, v64, v65
	v_cvt_pk_bf16_f32 v60, v60, v61
	v_cvt_pk_bf16_f32 v61, v68, v69
	v_lshl_add_u64 v[66:67], v[144:145], 0, s[2:3]
	s_nop 0
	v_addc_co_u32_e32 v63, vcc, 0, v145, vcc
	global_store_dwordx4 v[62:63], v[58:61], off
	s_mov_b64 s[2:3], -1
	v_pk_add_f32 v[6:7], v[6:7], 0 op_sel_hi:[1,0]
	v_pk_add_f32 v[58:59], v[48:49], 0 op_sel_hi:[1,0]
	v_pk_add_f32 v[48:49], v[46:47], 0 op_sel_hi:[1,0]
	v_cvt_pk_bf16_f32 v46, v54, v55
	v_cvt_pk_bf16_f32 v47, v56, v57
	s_nop 0
	v_cvt_pk_bf16_f32 v48, v48, v49
	v_cvt_pk_bf16_f32 v49, v58, v59
	global_store_dwordx4 v[66:67], v[46:49], off offset:256
	s_nop 1
	v_pk_add_f32 v[48:49], v[52:53], 0 op_sel_hi:[1,0]
	v_pk_add_f32 v[52:53], v[44:45], 0 op_sel_hi:[1,0]
	v_pk_add_f32 v[44:45], v[42:43], 0 op_sel_hi:[1,0]
	v_cvt_pk_bf16_f32 v42, v50, v51
	v_cvt_pk_bf16_f32 v43, v48, v49
	v_add_co_u32_e32 v48, vcc, s54, v144
	v_cvt_pk_bf16_f32 v44, v44, v45
	v_cvt_pk_bf16_f32 v45, v52, v53
	v_lshl_add_u64 v[46:47], v[144:145], 0, s[12:13]
	s_nop 0
	v_addc_co_u32_e32 v49, vcc, 0, v145, vcc
	global_store_dwordx4 v[48:49], v[42:45], off
	s_nop 1
	v_pk_add_f32 v[42:43], v[32:33], 0 op_sel_hi:[1,0]
	v_pk_add_f32 v[32:33], v[30:31], 0 op_sel_hi:[1,0]
	v_cvt_pk_bf16_f32 v30, v38, v39
	v_cvt_pk_bf16_f32 v31, v40, v41
	s_nop 0
	v_cvt_pk_bf16_f32 v32, v32, v33
	v_cvt_pk_bf16_f32 v33, v42, v43
	global_store_dwordx4 v[46:47], v[30:33], off offset:256
	s_nop 1
	v_pk_add_f32 v[32:33], v[36:37], 0 op_sel_hi:[1,0]
	v_pk_add_f32 v[36:37], v[28:29], 0 op_sel_hi:[1,0]
	v_pk_add_f32 v[28:29], v[26:27], 0 op_sel_hi:[1,0]
	v_cvt_pk_bf16_f32 v26, v34, v35
	v_cvt_pk_bf16_f32 v27, v32, v33
	v_add_co_u32_e32 v32, vcc, s55, v144
	v_cvt_pk_bf16_f32 v28, v28, v29
	v_cvt_pk_bf16_f32 v29, v36, v37
	v_lshl_add_u64 v[30:31], v[144:145], 0, s[14:15]
	s_nop 0
	v_addc_co_u32_e32 v33, vcc, 0, v145, vcc
	global_store_dwordx4 v[32:33], v[26:29], off
	s_nop 1
	v_pk_add_f32 v[26:27], v[16:17], 0 op_sel_hi:[1,0]
	v_pk_add_f32 v[16:17], v[14:15], 0 op_sel_hi:[1,0]
	v_cvt_pk_bf16_f32 v14, v22, v23
	v_cvt_pk_bf16_f32 v15, v24, v25
	s_nop 0
	v_cvt_pk_bf16_f32 v16, v16, v17
	v_cvt_pk_bf16_f32 v17, v26, v27
	global_store_dwordx4 v[30:31], v[14:17], off offset:256
	s_nop 1
	v_pk_add_f32 v[16:17], v[20:21], 0 op_sel_hi:[1,0]
	v_pk_add_f32 v[20:21], v[12:13], 0 op_sel_hi:[1,0]
	v_pk_add_f32 v[12:13], v[10:11], 0 op_sel_hi:[1,0]
	v_cvt_pk_bf16_f32 v10, v18, v19
	v_cvt_pk_bf16_f32 v11, v16, v17
	v_add_co_u32_e32 v16, vcc, s56, v144
	v_lshl_add_u64 v[14:15], v[144:145], 0, s[16:17]
	s_nop 0
	v_addc_co_u32_e32 v17, vcc, 0, v145, vcc
	v_cvt_pk_bf16_f32 v12, v12, v13
	v_cvt_pk_bf16_f32 v13, v20, v21
	global_store_dwordx4 v[16:17], v[10:13], off
	s_andn2_b64 vcc, exec, s[26:27]
	s_nop 0
	v_pk_add_f32 v[10:11], v[4:5], 0 op_sel_hi:[1,0]
	v_pk_add_f32 v[4:5], v[2:3], 0 op_sel_hi:[1,0]
	v_cvt_pk_bf16_f32 v2, v6, v7
	v_cvt_pk_bf16_f32 v3, v8, v9
	s_nop 0
	v_cvt_pk_bf16_f32 v4, v4, v5
	v_cvt_pk_bf16_f32 v5, v10, v11
	global_store_dwordx4 v[14:15], v[2:5], off offset:256
	s_cbranch_vccnz .LBB0_1230
	s_andn2_b64 vcc, exec, s[6:7]
	s_cbranch_vccnz .LBB0_1229
	s_barrier
	s_branch .LBB0_1229

.Lpk1444_exit:
	v_lshl_add_u32 v152, s55, 8, v1
	v_lshl_or_b32 v144, s54, 8, v147
	v_readlane_b32 s2, v252, 2
	v_ashrrev_i32_e32 v145, 31, v144
	v_readlane_b32 s3, v252, 3
	v_ashrrev_i32_e32 v153, 31, v152
	v_pk_add_f32 v[128:129], v[128:129], 0 op_sel_hi:[1,0]
	v_lshl_add_u64 v[154:155], v[144:145], 1, s[2:3]
	v_lshlrev_b64 v[144:145], 11, v[152:153]
	v_lshl_add_u64 v[144:145], v[154:155], 0, v[144:145]
	v_pk_add_f32 v[126:127], v[126:127], 0 op_sel_hi:[1,0]
	v_pk_add_f32 v[156:157], v[124:125], 0 op_sel_hi:[1,0]
	v_pk_add_f32 v[124:125], v[122:123], 0 op_sel_hi:[1,0]
	v_cvt_pk_bf16_f32 v122, v126, v127
	v_cvt_pk_bf16_f32 v123, v128, v129
	v_pk_add_f32 v[118:119], v[118:119], 0 op_sel_hi:[1,0]
	v_cvt_pk_bf16_f32 v124, v124, v125
	v_cvt_pk_bf16_f32 v125, v156, v157
	global_store_dwordx4 v[144:145], v[122:125], off
	v_pk_add_f32 v[120:121], v[120:121], 0 op_sel_hi:[1,0]
	v_pk_add_f32 v[114:115], v[114:115], 0 op_sel_hi:[1,0]
	v_pk_add_f32 v[122:123], v[112:113], 0 op_sel_hi:[1,0]
	v_pk_add_f32 v[112:113], v[110:111], 0 op_sel_hi:[1,0]
	v_cvt_pk_bf16_f32 v110, v118, v119
	v_cvt_pk_bf16_f32 v111, v120, v121
	v_pk_add_f32 v[102:103], v[102:103], 0 op_sel_hi:[1,0]
	v_cvt_pk_bf16_f32 v112, v112, v113
	v_cvt_pk_bf16_f32 v113, v122, v123
	global_store_dwordx4 v[144:145], v[110:113], off offset:256
	v_pk_add_f32 v[104:105], v[104:105], 0 op_sel_hi:[1,0]
	v_pk_add_f32 v[98:99], v[98:99], 0 op_sel_hi:[1,0]
	v_or_b32_e32 v110, 16, v152
	v_ashrrev_i32_e32 v111, 31, v110
	v_lshlrev_b64 v[110:111], 11, v[110:111]
	v_lshl_add_u64 v[110:111], v[154:155], 0, v[110:111]
	v_pk_add_f32 v[112:113], v[116:117], 0 op_sel_hi:[1,0]
	v_pk_add_f32 v[116:117], v[108:109], 0 op_sel_hi:[1,0]
	v_pk_add_f32 v[108:109], v[106:107], 0 op_sel_hi:[1,0]
	v_cvt_pk_bf16_f32 v106, v114, v115
	v_cvt_pk_bf16_f32 v107, v112, v113
	v_pk_add_f32 v[86:87], v[86:87], 0 op_sel_hi:[1,0]
	v_cvt_pk_bf16_f32 v108, v108, v109
	v_cvt_pk_bf16_f32 v109, v116, v117
	global_store_dwordx4 v[110:111], v[106:109], off
	v_pk_add_f32 v[88:89], v[88:89], 0 op_sel_hi:[1,0]
	v_pk_add_f32 v[82:83], v[82:83], 0 op_sel_hi:[1,0]
	v_pk_add_f32 v[106:107], v[96:97], 0 op_sel_hi:[1,0]
	v_pk_add_f32 v[96:97], v[94:95], 0 op_sel_hi:[1,0]
	v_cvt_pk_bf16_f32 v94, v102, v103
	v_cvt_pk_bf16_f32 v95, v104, v105
	v_pk_add_f32 v[72:73], v[72:73], 0 op_sel_hi:[1,0]
	v_cvt_pk_bf16_f32 v96, v96, v97
	v_cvt_pk_bf16_f32 v97, v106, v107
	global_store_dwordx4 v[110:111], v[94:97], off offset:256
	v_pk_add_f32 v[70:71], v[70:71], 0 op_sel_hi:[1,0]
	v_pk_add_f32 v[62:63], v[62:63], 0 op_sel_hi:[1,0]
	v_or_b32_e32 v94, 32, v152
	v_ashrrev_i32_e32 v95, 31, v94
	v_lshlrev_b64 v[94:95], 11, v[94:95]
	v_lshl_add_u64 v[94:95], v[154:155], 0, v[94:95]
	v_pk_add_f32 v[96:97], v[100:101], 0 op_sel_hi:[1,0]
	v_pk_add_f32 v[100:101], v[92:93], 0 op_sel_hi:[1,0]
	v_pk_add_f32 v[92:93], v[90:91], 0 op_sel_hi:[1,0]
	v_cvt_pk_bf16_f32 v90, v98, v99
	v_cvt_pk_bf16_f32 v91, v96, v97
	v_pk_add_f32 v[64:65], v[64:65], 0 op_sel_hi:[1,0]
	v_cvt_pk_bf16_f32 v92, v92, v93
	v_cvt_pk_bf16_f32 v93, v100, v101
	global_store_dwordx4 v[94:95], v[90:93], off
	v_pk_add_f32 v[56:57], v[56:57], 0 op_sel_hi:[1,0]
	v_pk_add_f32 v[54:55], v[54:55], 0 op_sel_hi:[1,0]
	v_pk_add_f32 v[90:91], v[80:81], 0 op_sel_hi:[1,0]
	v_pk_add_f32 v[80:81], v[78:79], 0 op_sel_hi:[1,0]
	v_cvt_pk_bf16_f32 v78, v86, v87
	v_cvt_pk_bf16_f32 v79, v88, v89
	v_pk_add_f32 v[50:51], v[50:51], 0 op_sel_hi:[1,0]
	v_cvt_pk_bf16_f32 v80, v80, v81
	v_cvt_pk_bf16_f32 v81, v90, v91
	global_store_dwordx4 v[94:95], v[78:81], off offset:256
	s_and_b64 vcc, exec, s[6:7]
	s_cbranch_vccz .LBB0_1447
	s_barrier
.LBB0_1447:
	v_pk_add_f32 v[40:41], v[40:41], 0 op_sel_hi:[1,0]
	v_pk_add_f32 v[38:39], v[38:39], 0 op_sel_hi:[1,0]
	v_or_b32_e32 v78, 48, v152
	v_ashrrev_i32_e32 v79, 31, v78
	v_lshlrev_b64 v[78:79], 11, v[78:79]
	v_lshl_add_u64 v[78:79], v[154:155], 0, v[78:79]
	v_pk_add_f32 v[80:81], v[84:85], 0 op_sel_hi:[1,0]
	v_pk_add_f32 v[84:85], v[76:77], 0 op_sel_hi:[1,0]
	v_pk_add_f32 v[76:77], v[74:75], 0 op_sel_hi:[1,0]
	v_cvt_pk_bf16_f32 v74, v82, v83
	v_cvt_pk_bf16_f32 v75, v80, v81
	v_pk_add_f32 v[34:35], v[34:35], 0 op_sel_hi:[1,0]
	v_cvt_pk_bf16_f32 v76, v76, v77
	v_cvt_pk_bf16_f32 v77, v84, v85
	global_store_dwordx4 v[78:79], v[74:77], off
	v_pk_add_f32 v[24:25], v[24:25], 0 op_sel_hi:[1,0]
	v_pk_add_f32 v[22:23], v[22:23], 0 op_sel_hi:[1,0]
	v_pk_add_f32 v[74:75], v[68:69], 0 op_sel_hi:[1,0]
	v_pk_add_f32 v[68:69], v[66:67], 0 op_sel_hi:[1,0]
	v_cvt_pk_bf16_f32 v66, v70, v71
	v_cvt_pk_bf16_f32 v67, v72, v73
	v_pk_add_f32 v[18:19], v[18:19], 0 op_sel_hi:[1,0]
	v_cvt_pk_bf16_f32 v68, v68, v69
	v_cvt_pk_bf16_f32 v69, v74, v75
	global_store_dwordx4 v[78:79], v[66:69], off offset:256
	s_mov_b64 s[2:3], -1
	v_pk_add_f32 v[8:9], v[8:9], 0 op_sel_hi:[1,0]
	v_pk_add_f32 v[68:69], v[60:61], 0 op_sel_hi:[1,0]
	v_pk_add_f32 v[60:61], v[58:59], 0 op_sel_hi:[1,0]
	v_cvt_pk_bf16_f32 v58, v62, v63
	v_add_co_u32_e32 v62, vcc, s48, v144
	v_cvt_pk_bf16_f32 v59, v64, v65
	v_cvt_pk_bf16_f32 v60, v60, v61
	v_cvt_pk_bf16_f32 v61, v68, v69
	v_lshl_add_u64 v[66:67], v[144:145], 0, s[8:9]
	s_nop 0
	v_addc_co_u32_e32 v63, vcc, 0, v145, vcc
	global_store_dwordx4 v[62:63], v[58:61], off
	v_pk_add_f32 v[6:7], v[6:7], 0 op_sel_hi:[1,0]
	s_nop 0
	v_pk_add_f32 v[58:59], v[48:49], 0 op_sel_hi:[1,0]
	v_pk_add_f32 v[48:49], v[46:47], 0 op_sel_hi:[1,0]
	v_cvt_pk_bf16_f32 v46, v54, v55
	v_cvt_pk_bf16_f32 v47, v56, v57
	s_nop 0
	v_cvt_pk_bf16_f32 v48, v48, v49
	v_cvt_pk_bf16_f32 v49, v58, v59
	global_store_dwordx4 v[66:67], v[46:49], off offset:256
	s_nop 1
	v_pk_add_f32 v[48:49], v[52:53], 0 op_sel_hi:[1,0]
	v_pk_add_f32 v[52:53], v[44:45], 0 op_sel_hi:[1,0]
	v_pk_add_f32 v[44:45], v[42:43], 0 op_sel_hi:[1,0]
	v_cvt_pk_bf16_f32 v42, v50, v51
	v_cvt_pk_bf16_f32 v43, v48, v49
	v_add_co_u32_e32 v48, vcc, s49, v144
	v_cvt_pk_bf16_f32 v44, v44, v45
	v_cvt_pk_bf16_f32 v45, v52, v53
	v_lshl_add_u64 v[46:47], v[144:145], 0, s[10:11]
	s_nop 0
	v_addc_co_u32_e32 v49, vcc, 0, v145, vcc
	global_store_dwordx4 v[48:49], v[42:45], off
	s_nop 1
	v_pk_add_f32 v[42:43], v[32:33], 0 op_sel_hi:[1,0]
	v_pk_add_f32 v[32:33], v[30:31], 0 op_sel_hi:[1,0]
	v_cvt_pk_bf16_f32 v30, v38, v39
	v_cvt_pk_bf16_f32 v31, v40, v41
	s_nop 0
	v_cvt_pk_bf16_f32 v32, v32, v33
	v_cvt_pk_bf16_f32 v33, v42, v43
	global_store_dwordx4 v[46:47], v[30:33], off offset:256
	s_nop 1
	v_pk_add_f32 v[32:33], v[36:37], 0 op_sel_hi:[1,0]
	v_pk_add_f32 v[36:37], v[28:29], 0 op_sel_hi:[1,0]
	v_pk_add_f32 v[28:29], v[26:27], 0 op_sel_hi:[1,0]
	v_cvt_pk_bf16_f32 v26, v34, v35
	v_cvt_pk_bf16_f32 v27, v32, v33
	v_add_co_u32_e32 v32, vcc, s50, v144
	v_cvt_pk_bf16_f32 v28, v28, v29
	v_cvt_pk_bf16_f32 v29, v36, v37
	v_lshl_add_u64 v[30:31], v[144:145], 0, s[12:13]
	s_nop 0
	v_addc_co_u32_e32 v33, vcc, 0, v145, vcc
	global_store_dwordx4 v[32:33], v[26:29], off
	s_nop 1
	v_pk_add_f32 v[26:27], v[16:17], 0 op_sel_hi:[1,0]
	v_pk_add_f32 v[16:17], v[14:15], 0 op_sel_hi:[1,0]
	v_cvt_pk_bf16_f32 v14, v22, v23
	v_cvt_pk_bf16_f32 v15, v24, v25
	s_nop 0
	v_cvt_pk_bf16_f32 v16, v16, v17
	v_cvt_pk_bf16_f32 v17, v26, v27
	global_store_dwordx4 v[30:31], v[14:17], off offset:256
	s_nop 1
	v_pk_add_f32 v[16:17], v[20:21], 0 op_sel_hi:[1,0]
	v_pk_add_f32 v[20:21], v[12:13], 0 op_sel_hi:[1,0]
	v_pk_add_f32 v[12:13], v[10:11], 0 op_sel_hi:[1,0]
	v_cvt_pk_bf16_f32 v10, v18, v19
	v_cvt_pk_bf16_f32 v11, v16, v17
	v_add_co_u32_e32 v16, vcc, s51, v144
	v_lshl_add_u64 v[14:15], v[144:145], 0, s[14:15]
	s_nop 0
	v_addc_co_u32_e32 v17, vcc, 0, v145, vcc
	v_cvt_pk_bf16_f32 v12, v12, v13
	v_cvt_pk_bf16_f32 v13, v20, v21
	global_store_dwordx4 v[16:17], v[10:13], off
	s_andn2_b64 vcc, exec, s[20:21]
	s_nop 0
	v_pk_add_f32 v[10:11], v[4:5], 0 op_sel_hi:[1,0]
	v_pk_add_f32 v[4:5], v[2:3], 0 op_sel_hi:[1,0]
	v_cvt_pk_bf16_f32 v2, v6, v7
	v_cvt_pk_bf16_f32 v3, v8, v9
	s_nop 0
	v_cvt_pk_bf16_f32 v4, v4, v5
	v_cvt_pk_bf16_f32 v5, v10, v11
	global_store_dwordx4 v[14:15], v[2:5], off offset:256
	s_cbranch_vccnz .LBB0_1435
	s_andn2_b64 vcc, exec, s[4:5]
	s_cbranch_vccnz .LBB0_1434
	s_barrier
	s_branch .LBB0_1434
